# P1 tail: third round re-cut into 164 half tiles (128x256), alt K loop without second-row-half MFMAs
# baseline (speedup 1.0000x reference)
; #define PG8_STAGE(bufoff, gbase, voff) do { _Pragma("unroll") for (int _i = 0; _i < 2; ++_i) \
;         __builtin_amdgcn_global_load_lds((const unsigned*)((const char*)(gbase) + (voff)[_i]), (LAS unsigned*)(lds + (bufoff) + ldsw + _i * 8192), 16, 0, 0); } while (0)
; #define PG8_WAIT_V(n) asm volatile("s_waitcnt vmcnt(" #n ")" ::: "memory")
; #define PG8_BAR __builtin_amdgcn_s_barrier()
; template <class Epi, class Sched>
; __device__ __forceinline__ void gemm_phase(LAS unsigned char* lds, const Gemm g, const Sched& S, const Epi& E) {
;     const int tid = threadIdx.x, wid = __builtin_amdgcn_readfirstlane(tid >> 6), lane = tid & 63, wr = wid >> 2, wc = wid & 3, fr = lane & 15, fq = lane >> 4;
;     const int K = g.K, nt = K / BK;
;     unsigned voffA[2], voffB[2];
; #pragma unroll
;     for (int i = 0; i < 2; ++i) { int R, C; stage_rc(tid * 16 + i * 8192, R, C); const int Rb = Epi::PERM ? ((R & ~31) + perm32(R & 31)) : R;
;         voffA[i] = (unsigned)(R * g.lda + C) * 2u; voffB[i] = (unsigned)(Rb * g.ldb + C) * 2u; }
;     const size_t kstep = (size_t)(BK * 2);
;     const size_t hstepA = (size_t)HALF * g.lda * 2, hstepB = (size_t)HALF * g.ldb * 2;
;     const size_t tstepA = 2 * hstepA, tstepB = 2 * hstepB;
;     const unsigned ldsw = (unsigned)wid * 1024u;
;     const int aoff = lds_byte(wr * 64 + fr, fq * 8), boff = lds_byte(wc * 32 + fr, fq * 8);
;     ...
;     Unit cur, nxt; int ui = 0;
;     if (!S.next(0, cur)) return;
;     f32x4 acc[2][2][4][2];
; #pragma unroll
;     for (int a = 0; a < 2; ++a)
; #pragma unroll
;         for (int b = 0; b < 2; ++b)
; #pragma unroll
;             for (int m = 0; m < 4; ++m)
; #pragma unroll
;                 for (int n = 0; n < 2; ++n) acc[a][b][m][n] = (f32x4){0.f, 0.f, 0.f, 0.f};
;     bf16x8 At[4][2], B0[2][2], B1[2][2];
;     const char* cA = (const char*)g.A + (size_t)cur.pm * tstepA + (size_t)cur.koffA * 2; const char* cB = (const char*)g.Bt + (size_t)cur.pn * tstepB + (size_t)cur.koffB * 2;
;     PG8_STAGE(PG8_SB(0, 0), cB, voffB); PG8_STAGE(PG8_SA(0, 0), cA, voffA); PG8_STAGE(PG8_SB(0, 1), cB + hstepB, voffB); PG8_STAGE(PG8_SA(0, 1), cA + hstepA, voffA);
;     if (wr == 1) PG8_BAR;
;     PG8_WAIT_V(4); PG8_BAR;
;     PG8_STAGE(PG8_SB(1, 0), cB + kstep, voffB); PG8_STAGE(PG8_SA(1, 0), cA + kstep, voffA); PG8_STAGE(PG8_SB(1, 1), cB + hstepB + kstep, voffB);
;     PG8_WAIT_V(6); PG8_BAR;
.LBB0_111:
	s_ashr_i32 s4, s6, 3
	s_waitcnt vmcnt(8)
	v_lshrrev_b32_e32 v2, 1, v196
	s_waitcnt vmcnt(6)
	v_and_b32_e32 v11, 24, v2
	v_lshrrev_b32_e32 v2, 5, v196
	s_add_i32 s4, s7, s4
	v_and_b32_e32 v2, 4, v2
	v_bfe_u32 v3, v196, 2, 2
	s_mul_hi_i32 s7, s4, 0x38e38e39
	v_lshlrev_b32_e32 v0, 4, v196
	v_and_b32_e32 v1, 32, v196
	v_bfe_u32 v10, v196, 2, 4
	v_or3_b32 v2, v2, v3, v11
	v_lshrrev_b32_e32 v3, 3, v196
	s_movk_i32 s6, 0x70
	s_lshr_b32 s8, s7, 31
	s_ashr_i32 s7, s7, 4
	v_bitop3_b32 v8, v0, v1, 48 bitop3:0x6c
	v_and_b32_e32 v9, 64, v196
	v_and_or_b32 v4, v3, s6, v10
	s_movk_i32 s6, 0x60
	v_add_u32_e32 v12, 0x2000, v0
	s_add_i32 s7, s7, s8
	v_or_b32_e32 v1, v8, v9
	v_and_or_b32 v3, v3, s6, v2
	v_lshrrev_b32_e32 v0, 7, v12
	s_movk_i32 s6, 0xf0
	s_lshl_b32 s10, s7, 2
	v_lshl_or_b32 v130, v3, 12, v1
	v_and_or_b32 v3, v0, s6, v10
	s_movk_i32 s6, 0xe0
	s_sub_i32 s8, 33, s10
	s_mulk_i32 s7, 0x48
	v_and_or_b32 v0, v0, s6, v2
	s_min_u32 s11, s8, 4
	s_sub_i32 s7, s4, s7
	v_lshl_or_b32 v128, v4, 12, v1
	v_lshl_or_b32 v132, v3, 12, v1
	v_lshl_or_b32 v134, v0, 12, v1
	s_sext_i32_i8 s4, s7
	v_cvt_f32_ubyte0_e32 v1, s11
	v_cvt_f32_i32_e32 v0, s4
	v_rcp_iflag_f32_e32 v2, v1
	s_lshr_b32 s6, s0, 6
	s_ashr_i32 s4, s4, 30
	s_lshr_b32 s5, s0, 8
	v_mul_f32_e32 v2, v0, v2
	v_trunc_f32_e32 v2, v2
	v_fma_f32 v0, -v2, v1, v0
	v_cvt_i32_f32_e32 v2, v2
	s_lshl_b32 s22, s6, 10
	s_or_b32 s4, s4, 1
	v_cmp_ge_f32_e64 s[8:9], |v0|, v1
	s_and_b64 s[8:9], s[8:9], exec
	s_cselect_b32 s4, s4, 0
	v_readfirstlane_b32 s8, v2
	s_add_i32 s4, s8, s4
	s_mul_i32 s8, s4, s11
	s_sub_i32 s7, s7, s8
	s_sext_i32_i8 s7, s7
	s_add_i32 s16, s10, s7
	s_ashr_i32 s17, s16, 31
	s_bfe_i64 s[10:11], s[4:5], 0x80000
	s_lshl_b64 s[8:9], s[16:17], 20
	s_lshl_b32 s16, s16, 1
	s_mov_b32 s70, 0
	s_lshl_b64 s[10:11], s[10:11], 20
	s_add_u32 s24, s90, s10
	s_addc_u32 s25, s91, s11
	s_add_i32 s17, s22, 0
	s_add_i32 m0, s17, 0x10000
	v_mov_b32_e32 v131, 0
	global_load_lds_dwordx4 v130, s[24:25]
	s_add_i32 m0, s17, 0x12000
	s_add_u32 s20, s46, s8
	global_load_lds_dwordx4 v134, s[24:25]
	s_addc_u32 s21, s47, s9
	s_mov_b32 m0, s17
	s_add_i32 s23, s17, 0x2000
	global_load_lds_dwordx4 v128, s[20:21]
	s_mov_b32 m0, s23
	s_add_u32 s8, s24, 0x80000
	global_load_lds_dwordx4 v132, s[20:21]
	s_addc_u32 s9, s25, 0
	s_add_i32 m0, s17, 0x14000
	v_mov_b32_e32 v135, v131
	global_load_lds_dwordx4 v130, s[8:9]
	s_add_i32 m0, s17, 0x16000
	v_mov_b32_e32 v129, v131
	global_load_lds_dwordx4 v134, s[8:9]
	s_add_u32 s8, s20, 0x80000
	s_addc_u32 s9, s21, 0
	s_add_i32 s29, s17, 0x4000
	s_mov_b32 m0, s29
	s_add_i32 s30, s17, 0x6000
	global_load_lds_dwordx4 v128, s[8:9]
	s_mov_b32 m0, s30
	v_mov_b32_e32 v133, v131
	global_load_lds_dwordx4 v132, s[8:9]
	s_mov_b32 s31, 0
	v_lshl_add_u64 v[6:7], s[24:25], 0, v[130:131]
	v_lshl_add_u64 v[4:5], s[24:25], 0, v[134:135]
	v_lshl_add_u64 v[2:3], s[20:21], 0, v[128:129]
	s_cmp_lg_u32 s5, 1
	v_lshl_add_u64 v[0:1], s[20:21], 0, v[132:133]
	s_cbranch_scc1 .LBB0_113
	s_barrier

;     __device__ bool next(int i, Unit& u) const {
;         const long L = (long)i * G + c; if (L >= nwg) return false;
;         int wgid = (int)L; { const int q = nwg / NXCD, r = nwg % NXCD, xcd = wgid % NXCD, off = wgid / NXCD; wgid = (xcd < r ? xcd * (q + 1) : r * (q + 1) + (xcd - r) * q) + off; }
; template <class Epi, class Sched>
; __device__ __forceinline__ void gemm_phase(LAS unsigned char* lds, const Gemm g, const Sched& S, const Epi& E) {
;     ...
;         const bool has_next = S.next(ui + 1, nxt);
.LBB0_114:
	s_add_i32 s31, s31, 1
	s_mul_i32 s4, s31, s35
	s_mul_hi_u32 s5, s31, s3
	s_add_i32 s5, s5, s4
	s_mul_i32 s4, s31, s3
	s_add_u32 s4, s4, s2
	s_addc_u32 s5, s5, s1
	s_mov_b32 s71, 0
	s_cmp_lg_u32 s31, 2
	s_cbranch_scc1 .Lp1_sched_done
	s_cmpk_lg_i32 s3, 0x100
	s_cbranch_scc1 .Lp1_sched_done
	s_lshr_b32 s4, s2, 1
	s_addk_i32 s4, 0x200
	s_mov_b32 s5, 0
	s_and_b32 s71, s2, 1
.Lp1_sched_done:
	v_cmp_gt_i64_e64 s[6:7], s[4:5], v[142:143]
	s_and_b64 vcc, exec, s[6:7]
	s_cbranch_vccnz .LBB0_120
	s_ashr_i32 s10, s4, 31
	s_lshr_b32 s10, s10, 29
	s_add_i32 s12, s4, s10
	s_and_b32 s10, s12, -8
	s_sub_i32 s13, s4, s10
	s_cmp_gt_i32 s13, 1
	s_mov_b64 s[10:11], -1
	s_cbranch_scc0 .LBB0_117
	s_mul_i32 s10, s13, 0x4a
	s_add_i32 s14, s10, 2
	s_mov_b64 s[10:11], 0

;     __device__ bool next(int i, Unit& u) const {
;     ...
;         int wgid = (int)L; { const int q = nwg / NXCD, r = nwg % NXCD, xcd = wgid % NXCD, off = wgid / NXCD; wgid = (xcd < r ? xcd * (q + 1) : r * (q + 1) + (xcd - r) * q) + off; }
;         const int nig = WGM * nN, gid = wgid / nig, fm = gid * WGM, gsz = (nM - fm) < WGM ? (nM - fm) : WGM;
;         u.pm = fm + ((wgid % nig) % gsz); u.pn = (wgid % nig) / gsz; u.ks = 0; u.koffA = 0; u.koffB = 0; return true;
; template <class Epi, class Sched>
; __device__ __forceinline__ void gemm_phase(LAS unsigned char* lds, const Gemm g, const Sched& S, const Epi& E) {
;     ...
; #pragma unroll
;         for (int a = 0; a < 2; ++a)
; #pragma unroll
;             for (int b = 0; b < 2; ++b)
; #pragma unroll
;                 for (int m = 0; m < 4; ++m)
; #pragma unroll
;                     for (int n = 0; n < 2; ++n) acc[a][b][m][n] = (f32x4){0.f, 0.f, 0.f, 0.f};
;         cur = nxt; cA = nA; cB = nB; ++ui;
.LBB0_119:
	s_ashr_i32 s10, s12, 3
	s_add_i32 s10, s14, s10
	s_mul_hi_i32 s11, s10, 0x38e38e39
	s_lshr_b32 s12, s11, 31
	s_ashr_i32 s11, s11, 4
	s_add_i32 s11, s11, s12
	s_lshl_b32 s12, s11, 2
	s_sub_i32 s13, 33, s12
	s_min_i32 s13, s13, 4
	s_abs_i32 s14, s13
	v_cvt_f32_u32_e32 v0, s14
	s_sub_i32 s18, 0, s14
	s_mulk_i32 s11, 0x48
	s_sub_i32 s11, s10, s11
	v_rcp_iflag_f32_e32 v0, v0
	s_abs_i32 s10, s11
	s_xor_b32 s15, s11, s13
	s_ashr_i32 s15, s15, 31
	v_mul_f32_e32 v0, 0x4f7ffffe, v0
	v_cvt_u32_f32_e32 v0, v0
	s_nop 0
	v_readfirstlane_b32 s19, v0
	s_mul_i32 s18, s18, s19
	s_mul_hi_u32 s18, s19, s18
	s_add_i32 s19, s19, s18
	s_mul_hi_u32 s18, s10, s19
	s_mul_i32 s19, s18, s14
	s_sub_i32 s10, s10, s19
	s_add_i32 s26, s18, 1
	s_sub_i32 s19, s10, s14
	s_cmp_ge_u32 s10, s14
	s_cselect_b32 s18, s26, s18
	s_cselect_b32 s10, s19, s10
	s_add_i32 s19, s18, 1
	s_cmp_ge_u32 s10, s14
	s_cselect_b32 s10, s19, s18
	s_xor_b32 s10, s10, s15
	s_sub_i32 s10, s10, s15
	s_mul_i32 s13, s10, s13
	s_sub_i32 s11, s11, s13
	s_add_i32 s12, s12, s11
	s_lshl_b32 s12, s12, 1
	s_add_i32 s12, s12, s71
.LBB0_120:
	s_ashr_i32 s13, s12, 31
	v_cmp_lt_i64_e32 vcc, s[4:5], v[140:141]
	s_lshl_b64 s[4:5], s[12:13], 19
	s_add_u32 s14, s46, s4
	s_addc_u32 s15, s47, s5
	s_and_b64 s[4:5], vcc, exec
	s_cselect_b32 s4, s15, s21
	s_cselect_b32 s5, s14, s20
	s_ashr_i32 s11, s10, 31
	s_lshl_b64 s[18:19], s[10:11], 20
	s_add_u32 s18, s90, s18
	s_addc_u32 s19, s91, s19
	s_and_b64 s[26:27], vcc, exec
	s_cselect_b32 s11, s19, s25
	s_cselect_b32 s13, s18, s24
	s_add_u32 s20, s20, 0x80080
	s_addc_u32 s21, s21, 0
	s_add_u32 s62, s24, 0x100
	v_mov_b32_e32 v0, 0
	s_addc_u32 s63, s25, 0
	s_mov_b32 s64, -2
	v_mov_b32_e32 v1, v0
	v_mov_b64_e32 v[2:3], 0
	v_mov_b64_e32 v[4:5], 0
	v_mov_b64_e32 v[6:7], 0
	v_mov_b64_e32 v[8:9], 0
	v_mov_b64_e32 v[10:11], 0
	v_mov_b64_e32 v[12:13], 0
	v_mov_b64_e32 v[14:15], 0
	v_mov_b64_e32 v[16:17], 0
	v_mov_b64_e32 v[18:19], 0
	v_mov_b64_e32 v[20:21], 0
	v_mov_b64_e32 v[22:23], 0
	v_mov_b64_e32 v[24:25], 0
	v_mov_b64_e32 v[26:27], 0
	v_mov_b64_e32 v[28:29], 0
	v_mov_b64_e32 v[30:31], 0
	v_mov_b32_e32 v48, v0
	v_mov_b32_e32 v49, v0
	v_mov_b32_e32 v50, v0
	v_mov_b32_e32 v51, v0
	v_mov_b32_e32 v52, v0
	v_mov_b32_e32 v53, v0
	v_mov_b32_e32 v54, v0
	v_mov_b32_e32 v55, v0
	v_mov_b32_e32 v64, v0
	v_mov_b32_e32 v65, v0
	v_mov_b32_e32 v66, v0
	v_mov_b32_e32 v67, v0
	v_mov_b32_e32 v72, v0
	v_mov_b32_e32 v73, v0
	v_mov_b32_e32 v74, v0
	v_mov_b32_e32 v75, v0
	v_mov_b32_e32 v80, v0
	v_mov_b32_e32 v81, v0
	v_mov_b32_e32 v82, v0
	v_mov_b32_e32 v83, v0
	v_mov_b32_e32 v84, v0
	v_mov_b32_e32 v85, v0
	v_mov_b32_e32 v86, v0
	v_mov_b32_e32 v87, v0
	v_mov_b32_e32 v88, v0
	v_mov_b32_e32 v89, v0
	v_mov_b32_e32 v90, v0
	v_mov_b32_e32 v91, v0
	v_mov_b32_e32 v92, v0
	v_mov_b32_e32 v93, v0
	v_mov_b32_e32 v94, v0
	v_mov_b32_e32 v95, v0
	v_mov_b32_e32 v32, v0
	v_mov_b32_e32 v33, v0
	v_mov_b32_e32 v34, v0
	v_mov_b32_e32 v35, v0
	v_mov_b32_e32 v36, v0
	v_mov_b32_e32 v37, v0
	v_mov_b32_e32 v38, v0
	v_mov_b32_e32 v39, v0
	v_mov_b32_e32 v40, v0
	v_mov_b32_e32 v41, v0
	v_mov_b32_e32 v42, v0
	v_mov_b32_e32 v43, v0
	v_mov_b32_e32 v44, v0
	v_mov_b32_e32 v45, v0
	v_mov_b32_e32 v46, v0
	v_mov_b32_e32 v47, v0
	v_mov_b32_e32 v56, v0
	v_mov_b32_e32 v57, v0
	v_mov_b32_e32 v58, v0
	v_mov_b32_e32 v59, v0
	v_mov_b32_e32 v60, v0
	v_mov_b32_e32 v61, v0
	v_mov_b32_e32 v62, v0
	v_mov_b32_e32 v63, v0
	v_mov_b32_e32 v68, v0
	v_mov_b32_e32 v69, v0
	v_mov_b32_e32 v70, v0
	v_mov_b32_e32 v71, v0
	v_mov_b32_e32 v76, v0
	v_mov_b32_e32 v77, v0
	v_mov_b32_e32 v78, v0
	v_mov_b32_e32 v79, v0
	v_mov_b32_e32 v96, v0
	v_mov_b32_e32 v97, v0
	v_mov_b32_e32 v98, v0
	v_mov_b32_e32 v99, v0
	v_mov_b32_e32 v100, v0
	v_mov_b32_e32 v101, v0
	v_mov_b32_e32 v102, v0
	v_mov_b32_e32 v103, v0
	v_mov_b32_e32 v104, v0
	v_mov_b32_e32 v105, v0
	v_mov_b32_e32 v106, v0
	v_mov_b32_e32 v107, v0
	v_mov_b32_e32 v108, v0
	v_mov_b32_e32 v109, v0
	v_mov_b32_e32 v110, v0
	v_mov_b32_e32 v111, v0
	v_mov_b32_e32 v112, v0
	v_mov_b32_e32 v113, v0
	v_mov_b32_e32 v114, v0
	v_mov_b32_e32 v115, v0
	v_mov_b32_e32 v116, v0
	v_mov_b32_e32 v117, v0
	v_mov_b32_e32 v118, v0
	v_mov_b32_e32 v119, v0
	v_mov_b32_e32 v120, v0
	v_mov_b32_e32 v121, v0
	v_mov_b32_e32 v122, v0
	v_mov_b32_e32 v123, v0
	v_mov_b32_e32 v124, v0
	v_mov_b32_e32 v125, v0
	v_mov_b32_e32 v126, v0
	v_mov_b32_e32 v127, v0
	s_cmp_lg_u32 s70, 0
	s_cbranch_scc1 .Lp1h_loop
; #define PG8_STAGE(bufoff, gbase, voff) do { _Pragma("unroll") for (int _i = 0; _i < 2; ++_i) \
;         __builtin_amdgcn_global_load_lds((const unsigned*)((const char*)(gbase) + (voff)[_i]), (LAS unsigned*)(lds + (bufoff) + ldsw + _i * 8192), 16, 0, 0); } while (0)
; #define PG8_LDA(dst, b, h) do { _Pragma("unroll") for (int m = 0; m < 4; ++m) _Pragma("unroll") for (int k = 0; k < 2; ++k) dst[m][k] = *(const LAS bf16x8*)(lds + PG8_SA(b, h) + aoff + m * 2048 + k * 1024); } while (0)
; #define PG8_LDB(dst, b, h) do { _Pragma("unroll") for (int n = 0; n < 2; ++n) _Pragma("unroll") for (int k = 0; k < 2; ++k) dst[n][k] = *(const LAS bf16x8*)(lds + PG8_SB(b, h) + boff + n * 2048 + k * 1024); } while (0)
; #define PG8_MMA(ai, bj, At, Bt) do { __builtin_amdgcn_s_setprio(1); _Pragma("unroll") for (int m = 0; m < 4; ++m) _Pragma("unroll") for (int n = 0; n < 2; ++n) _Pragma("unroll") for (int k = 0; k < 2; ++k) \
;         acc[ai][bj][m][n] = __builtin_amdgcn_mfma_f32_16x16x32_bf16(Bt[n][k], At[m][k], acc[ai][bj][m][n], 0, 0, 0); __builtin_amdgcn_s_setprio(0); } while (0)
; #define PG8_WAIT_V(n) asm volatile("s_waitcnt vmcnt(" #n ")" ::: "memory")
; #define PG8_WAIT_L(n) asm volatile("s_waitcnt lgkmcnt(" #n ")" ::: "memory")
; template <class Epi, class Sched>
; __device__ __forceinline__ void gemm_phase(LAS unsigned char* lds, const Gemm g, const Sched& S, const Epi& E) {
;     ...
;         for (int t = 0; t < nt; t += 2) {
;             const bool last = (t == nt - 2);
;             const char* a1 = cA + (size_t)(t + 1) * kstep;
;             const char* a2 = last ? nA : cA + (size_t)(t + 2) * kstep; const char* b2 = last ? nB : cB + (size_t)(t + 2) * kstep;
;             const char* a3 = a2 + kstep; const char* b3 = b2 + kstep;
;             PG8_LDB(B0, 0, 0); PG8_SCHED; PG8_LDA(At, 0, 0); PG8_STAGE(PG8_SA(1, 1), a1 + hstepA, voffA);
;             PG8_WAIT_L(8); PG8_BAR; PG8_WAIT_L(0); PG8_MMA(0, 0, At, B0); PG8_BAR; PG8_SCHED;
;             PG8_LDB(B1, 0, 1); PG8_STAGE(PG8_SB(0, 0), b2, voffB);
;             PG8_BAR; PG8_WAIT_L(0); PG8_MMA(0, 1, At, B1); PG8_BAR;
;             PG8_LDA(At, 0, 1); PG8_STAGE(PG8_SA(0, 0), a2, voffA);
;             PG8_BAR; PG8_WAIT_L(0); PG8_MMA(1, 0, At, B0); PG8_BAR; PG8_SCHED;
;             PG8_STAGE(PG8_SB(0, 1), b2 + hstepB, voffB);
;             PG8_WAIT_V(6); PG8_BAR; PG8_MMA(1, 1, At, B1); PG8_BAR;
.LBB0_121:
	ds_read_b128 v[150:153], v147
	ds_read_b128 v[154:157], v147 offset:1024
	ds_read_b128 v[158:161], v147 offset:2048
	ds_read_b128 v[162:165], v147 offset:3072
	s_add_u32 s24, s20, 0xfff80080
	s_addc_u32 s25, s21, -1
	s_cmp_eq_u32 s64, 28
	s_cselect_b32 s27, s4, s25
	s_cselect_b32 s26, s5, s24
	s_cselect_b32 s25, s11, s63
	s_cselect_b32 s24, s13, s62
	v_lshl_add_u64 v[194:195], s[20:21], 0, v[136:137]
	s_add_i32 m0, s17, 0xc000
	ds_read_b128 v[166:169], v148
	ds_read_b128 v[170:173], v148 offset:1024
	ds_read_b128 v[174:177], v148 offset:2048
	ds_read_b128 v[178:181], v148 offset:3072
	ds_read_b128 v[182:185], v148 offset:4096
	ds_read_b128 v[186:189], v148 offset:5120
	ds_read_b128 v[190:193], v148 offset:6144
	ds_read_b128 v[198:201], v148 offset:7168
	global_load_lds_dwordx4 v[194:195], off
	v_lshl_add_u64 v[194:195], s[20:21], 0, v[138:139]
	s_add_i32 m0, s17, 0xe000
	s_nop 0
	global_load_lds_dwordx4 v[194:195], off
	s_waitcnt lgkmcnt(8)
	s_barrier
	s_waitcnt lgkmcnt(0)
	s_setprio 1
	s_waitcnt lgkmcnt(0)
	v_mfma_f32_16x16x32_bf16 v[124:127], v[150:153], v[166:169], v[124:127]
	v_mfma_f32_16x16x32_bf16 v[120:123], v[158:161], v[166:169], v[120:123]
	v_mfma_f32_16x16x32_bf16 v[116:119], v[150:153], v[174:177], v[116:119]
	v_mfma_f32_16x16x32_bf16 v[112:115], v[158:161], v[174:177], v[112:115]
	v_mfma_f32_16x16x32_bf16 v[108:111], v[150:153], v[182:185], v[108:111]
	v_mfma_f32_16x16x32_bf16 v[104:107], v[158:161], v[182:185], v[104:107]
	v_mfma_f32_16x16x32_bf16 v[100:103], v[150:153], v[190:193], v[100:103]
	v_mfma_f32_16x16x32_bf16 v[96:99], v[158:161], v[190:193], v[96:99]
	v_mfma_f32_16x16x32_bf16 v[124:127], v[154:157], v[170:173], v[124:127]
	v_mfma_f32_16x16x32_bf16 v[120:123], v[162:165], v[170:173], v[120:123]
	v_mfma_f32_16x16x32_bf16 v[116:119], v[154:157], v[178:181], v[116:119]
	v_mfma_f32_16x16x32_bf16 v[112:115], v[162:165], v[178:181], v[112:115]
	v_mfma_f32_16x16x32_bf16 v[108:111], v[154:157], v[186:189], v[108:111]
	v_mfma_f32_16x16x32_bf16 v[104:107], v[162:165], v[186:189], v[104:107]
	v_mfma_f32_16x16x32_bf16 v[100:103], v[154:157], v[198:201], v[100:103]
	v_mfma_f32_16x16x32_bf16 v[96:99], v[162:165], v[198:201], v[96:99]
	s_setprio 0
	s_barrier
	s_add_i32 s65, s50, s22
	v_lshl_add_u64 v[194:195], s[24:25], 0, v[130:131]
	s_mov_b32 m0, s65
	ds_read_b128 v[202:205], v149
	ds_read_b128 v[206:209], v149 offset:1024
	ds_read_b128 v[210:213], v149 offset:2048
	ds_read_b128 v[214:217], v149 offset:3072
	global_load_lds_dwordx4 v[194:195], off
	v_lshl_add_u64 v[218:219], s[24:25], 0, v[134:135]
	s_add_i32 m0, s65, 0x2000
	s_nop 0
	global_load_lds_dwordx4 v[218:219], off
	s_barrier
	s_waitcnt lgkmcnt(0)
	s_setprio 1
	s_waitcnt lgkmcnt(0)
	v_mfma_f32_16x16x32_bf16 v[76:79], v[202:205], v[166:169], v[76:79]
	v_mfma_f32_16x16x32_bf16 v[68:71], v[210:213], v[166:169], v[68:71]
	v_mfma_f32_16x16x32_bf16 v[60:63], v[202:205], v[174:177], v[60:63]
	v_mfma_f32_16x16x32_bf16 v[56:59], v[210:213], v[174:177], v[56:59]
	v_mfma_f32_16x16x32_bf16 v[44:47], v[202:205], v[182:185], v[44:47]
	v_mfma_f32_16x16x32_bf16 v[40:43], v[210:213], v[182:185], v[40:43]
	v_mfma_f32_16x16x32_bf16 v[36:39], v[202:205], v[190:193], v[36:39]
	v_mfma_f32_16x16x32_bf16 v[32:35], v[210:213], v[190:193], v[32:35]
	v_mfma_f32_16x16x32_bf16 v[76:79], v[206:209], v[170:173], v[76:79]
	v_mfma_f32_16x16x32_bf16 v[68:71], v[214:217], v[170:173], v[68:71]
	v_mfma_f32_16x16x32_bf16 v[60:63], v[206:209], v[178:181], v[60:63]
	v_mfma_f32_16x16x32_bf16 v[56:59], v[214:217], v[178:181], v[56:59]
	v_mfma_f32_16x16x32_bf16 v[44:47], v[206:209], v[186:189], v[44:47]
	v_mfma_f32_16x16x32_bf16 v[40:43], v[214:217], v[186:189], v[40:43]
	v_mfma_f32_16x16x32_bf16 v[36:39], v[206:209], v[198:201], v[36:39]
	v_mfma_f32_16x16x32_bf16 v[32:35], v[214:217], v[198:201], v[32:35]
	s_setprio 0
	s_mov_b32 m0, s17
	v_lshl_add_u64 v[220:221], s[26:27], 0, v[128:129]
	s_barrier
	ds_read_b128 v[166:169], v148 offset:16384
	ds_read_b128 v[170:173], v148 offset:17408
	ds_read_b128 v[174:177], v148 offset:18432
	ds_read_b128 v[178:181], v148 offset:19456
	ds_read_b128 v[182:185], v148 offset:20480
	ds_read_b128 v[186:189], v148 offset:21504
	ds_read_b128 v[190:193], v148 offset:22528
	ds_read_b128 v[198:201], v148 offset:23552
	global_load_lds_dwordx4 v[220:221], off
	v_lshl_add_u64 v[222:223], s[26:27], 0, v[132:133]
	s_mov_b32 m0, s23
	s_nop 0
	global_load_lds_dwordx4 v[222:223], off
	s_barrier
	s_waitcnt lgkmcnt(0)
	s_setprio 1
	s_waitcnt lgkmcnt(0)
	v_mfma_f32_16x16x32_bf16 v[92:95], v[150:153], v[166:169], v[92:95]
	v_mfma_f32_16x16x32_bf16 v[88:91], v[158:161], v[166:169], v[88:91]
	v_mfma_f32_16x16x32_bf16 v[84:87], v[150:153], v[174:177], v[84:87]
	v_mfma_f32_16x16x32_bf16 v[80:83], v[158:161], v[174:177], v[80:83]
	v_mfma_f32_16x16x32_bf16 v[72:75], v[150:153], v[182:185], v[72:75]
	v_mfma_f32_16x16x32_bf16 v[64:67], v[158:161], v[182:185], v[64:67]
	v_mfma_f32_16x16x32_bf16 v[52:55], v[150:153], v[190:193], v[52:55]
	v_mfma_f32_16x16x32_bf16 v[48:51], v[158:161], v[190:193], v[48:51]
	v_mfma_f32_16x16x32_bf16 v[92:95], v[154:157], v[170:173], v[92:95]
	v_mfma_f32_16x16x32_bf16 v[88:91], v[162:165], v[170:173], v[88:91]
	v_mfma_f32_16x16x32_bf16 v[84:87], v[154:157], v[178:181], v[84:87]
	v_mfma_f32_16x16x32_bf16 v[80:83], v[162:165], v[178:181], v[80:83]
	v_mfma_f32_16x16x32_bf16 v[72:75], v[154:157], v[186:189], v[72:75]
	v_mfma_f32_16x16x32_bf16 v[64:67], v[162:165], v[186:189], v[64:67]
	v_mfma_f32_16x16x32_bf16 v[52:55], v[154:157], v[198:201], v[52:55]
	v_mfma_f32_16x16x32_bf16 v[48:51], v[162:165], v[198:201], v[48:51]
	s_setprio 0
	s_barrier
; #define PG8_STAGE(bufoff, gbase, voff) do { _Pragma("unroll") for (int _i = 0; _i < 2; ++_i) \
;         __builtin_amdgcn_global_load_lds((const unsigned*)((const char*)(gbase) + (voff)[_i]), (LAS unsigned*)(lds + (bufoff) + ldsw + _i * 8192), 16, 0, 0); } while (0)
; #define PG8_LDA(dst, b, h) do { _Pragma("unroll") for (int m = 0; m < 4; ++m) _Pragma("unroll") for (int k = 0; k < 2; ++k) dst[m][k] = *(const LAS bf16x8*)(lds + PG8_SA(b, h) + aoff + m * 2048 + k * 1024); } while (0)
; #define PG8_LDB(dst, b, h) do { _Pragma("unroll") for (int n = 0; n < 2; ++n) _Pragma("unroll") for (int k = 0; k < 2; ++k) dst[n][k] = *(const LAS bf16x8*)(lds + PG8_SB(b, h) + boff + n * 2048 + k * 1024); } while (0)
; #define PG8_MMA(ai, bj, At, Bt) do { __builtin_amdgcn_s_setprio(1); _Pragma("unroll") for (int m = 0; m < 4; ++m) _Pragma("unroll") for (int n = 0; n < 2; ++n) _Pragma("unroll") for (int k = 0; k < 2; ++k) \
;         acc[ai][bj][m][n] = __builtin_amdgcn_mfma_f32_16x16x32_bf16(Bt[n][k], At[m][k], acc[ai][bj][m][n], 0, 0, 0); __builtin_amdgcn_s_setprio(0); } while (0)
; #define PG8_WAIT_V(n) asm volatile("s_waitcnt vmcnt(" #n ")" ::: "memory")
; #define PG8_WAIT_L(n) asm volatile("s_waitcnt lgkmcnt(" #n ")" ::: "memory")
; #define PG8_BAR __builtin_amdgcn_s_barrier()
; #define PG8_SCHED __builtin_amdgcn_sched_barrier(0)
; template <class Epi, class Sched>
; __device__ __forceinline__ void gemm_phase(LAS unsigned char* lds, const Gemm g, const Sched& S, const Epi& E) {
;     ...
;             PG8_LDA(At, 0, 1); PG8_STAGE(PG8_SA(0, 0), a2, voffA);
;             PG8_BAR; PG8_WAIT_L(0); PG8_MMA(1, 0, At, B0); PG8_BAR; PG8_SCHED;
;             PG8_STAGE(PG8_SB(0, 1), b2 + hstepB, voffB);
;             PG8_WAIT_V(6); PG8_BAR; PG8_MMA(1, 1, At, B1); PG8_BAR;
;             PG8_LDB(B0, 1, 0); PG8_SCHED; PG8_LDA(At, 1, 0); PG8_STAGE(PG8_SA(0, 1), a2 + hstepA, voffA);
;             PG8_WAIT_L(8); PG8_BAR; PG8_WAIT_L(0); PG8_MMA(0, 0, At, B0); PG8_BAR; PG8_SCHED;
;             PG8_LDB(B1, 1, 1); PG8_STAGE(PG8_SB(1, 0), b3, voffB);
;             PG8_BAR; PG8_WAIT_L(0); PG8_MMA(0, 1, At, B1); PG8_BAR;
;             PG8_LDA(At, 1, 1); PG8_STAGE(PG8_SA(1, 0), a3, voffA);
;             PG8_BAR; PG8_WAIT_L(0); PG8_MMA(1, 0, At, B0); PG8_BAR; PG8_SCHED;
	s_add_u32 s68, s24, 0x80000
	s_addc_u32 s69, s25, 0
	s_add_i32 s65, s51, s22
	v_lshl_add_u64 v[150:151], s[68:69], 0, v[130:131]
	s_mov_b32 m0, s65
	s_nop 0
	global_load_lds_dwordx4 v[150:151], off
	v_lshl_add_u64 v[150:151], s[68:69], 0, v[134:135]
	s_add_i32 m0, s65, 0x2000
	s_nop 0
	global_load_lds_dwordx4 v[150:151], off
	s_waitcnt vmcnt(6)
	s_barrier
	s_setprio 1
	v_mfma_f32_16x16x32_bf16 v[28:31], v[202:205], v[166:169], v[28:31]
	v_mfma_f32_16x16x32_bf16 v[24:27], v[210:213], v[166:169], v[24:27]
	v_mfma_f32_16x16x32_bf16 v[20:23], v[202:205], v[174:177], v[20:23]
	v_mfma_f32_16x16x32_bf16 v[16:19], v[210:213], v[174:177], v[16:19]
	v_mfma_f32_16x16x32_bf16 v[12:15], v[202:205], v[182:185], v[12:15]
	v_mfma_f32_16x16x32_bf16 v[8:11], v[210:213], v[182:185], v[8:11]
	v_mfma_f32_16x16x32_bf16 v[4:7], v[202:205], v[190:193], v[4:7]
	v_mfma_f32_16x16x32_bf16 v[0:3], v[210:213], v[190:193], v[0:3]
	v_mfma_f32_16x16x32_bf16 v[28:31], v[206:209], v[170:173], v[28:31]
	v_mfma_f32_16x16x32_bf16 v[24:27], v[214:217], v[170:173], v[24:27]
	v_mfma_f32_16x16x32_bf16 v[20:23], v[206:209], v[178:181], v[20:23]
	v_mfma_f32_16x16x32_bf16 v[16:19], v[214:217], v[178:181], v[16:19]
	v_mfma_f32_16x16x32_bf16 v[12:15], v[206:209], v[186:189], v[12:15]
	v_mfma_f32_16x16x32_bf16 v[8:11], v[214:217], v[186:189], v[8:11]
	v_mfma_f32_16x16x32_bf16 v[4:7], v[206:209], v[198:201], v[4:7]
	v_mfma_f32_16x16x32_bf16 v[0:3], v[214:217], v[198:201], v[0:3]
	s_setprio 0
	s_add_i32 s65, 0, 0x18000
	v_add_u32_e32 v162, s65, v145
	s_barrier
	ds_read_b128 v[150:153], v162
	ds_read_b128 v[154:157], v162 offset:1024
	ds_read_b128 v[158:161], v162 offset:2048
	ds_read_b128 v[162:165], v162 offset:3072
	s_add_u32 s26, s26, 0x80000
	s_addc_u32 s27, s27, 0
	s_mov_b32 m0, s29
	v_lshl_add_u64 v[202:203], s[26:27], 0, v[128:129]
	ds_read_b128 v[166:169], v148 offset:32768
	ds_read_b128 v[170:173], v148 offset:33792
	ds_read_b128 v[174:177], v148 offset:34816
	ds_read_b128 v[178:181], v148 offset:35840
	ds_read_b128 v[182:185], v148 offset:36864
	ds_read_b128 v[186:189], v148 offset:37888
	ds_read_b128 v[190:193], v148 offset:38912
	ds_read_b128 v[198:201], v148 offset:39936
	global_load_lds_dwordx4 v[202:203], off
	v_lshl_add_u64 v[202:203], s[26:27], 0, v[132:133]
	s_mov_b32 m0, s30
	s_nop 0
	global_load_lds_dwordx4 v[202:203], off
	s_waitcnt lgkmcnt(8)
	s_barrier
	s_waitcnt lgkmcnt(0)
	s_setprio 1
	s_waitcnt lgkmcnt(0)
	v_mfma_f32_16x16x32_bf16 v[124:127], v[150:153], v[166:169], v[124:127]
	v_mfma_f32_16x16x32_bf16 v[120:123], v[158:161], v[166:169], v[120:123]
	v_mfma_f32_16x16x32_bf16 v[116:119], v[150:153], v[174:177], v[116:119]
	v_mfma_f32_16x16x32_bf16 v[112:115], v[158:161], v[174:177], v[112:115]
	v_mfma_f32_16x16x32_bf16 v[108:111], v[150:153], v[182:185], v[108:111]
	v_mfma_f32_16x16x32_bf16 v[104:107], v[158:161], v[182:185], v[104:107]
	v_mfma_f32_16x16x32_bf16 v[100:103], v[150:153], v[190:193], v[100:103]
	v_mfma_f32_16x16x32_bf16 v[96:99], v[158:161], v[190:193], v[96:99]
	v_mfma_f32_16x16x32_bf16 v[124:127], v[154:157], v[170:173], v[124:127]
	v_mfma_f32_16x16x32_bf16 v[120:123], v[162:165], v[170:173], v[120:123]
	v_mfma_f32_16x16x32_bf16 v[116:119], v[154:157], v[178:181], v[116:119]
	v_mfma_f32_16x16x32_bf16 v[112:115], v[162:165], v[178:181], v[112:115]
	v_mfma_f32_16x16x32_bf16 v[108:111], v[154:157], v[186:189], v[108:111]
	v_mfma_f32_16x16x32_bf16 v[104:107], v[162:165], v[186:189], v[104:107]
	v_mfma_f32_16x16x32_bf16 v[100:103], v[154:157], v[198:201], v[100:103]
	v_mfma_f32_16x16x32_bf16 v[96:99], v[162:165], v[198:201], v[96:99]
	s_setprio 0
	s_barrier
	s_add_i32 s26, 0, 0x1c000
	s_add_i32 s27, s65, s22
	v_add_u32_e32 v197, s26, v145
	v_lshl_add_u64 v[194:195], v[194:195], 0, s[8:9]
	s_mov_b32 m0, s27
	ds_read_b128 v[202:205], v197
	ds_read_b128 v[206:209], v197 offset:1024
	ds_read_b128 v[210:213], v197 offset:2048
	ds_read_b128 v[214:217], v197 offset:3072
	global_load_lds_dwordx4 v[194:195], off
	v_lshl_add_u64 v[194:195], v[218:219], 0, s[8:9]
	s_add_i32 m0, s27, 0x2000
	s_nop 0
	global_load_lds_dwordx4 v[194:195], off
	s_barrier
	s_waitcnt lgkmcnt(0)
	s_setprio 1
	s_waitcnt lgkmcnt(0)
	v_mfma_f32_16x16x32_bf16 v[76:79], v[202:205], v[166:169], v[76:79]
	v_mfma_f32_16x16x32_bf16 v[68:71], v[210:213], v[166:169], v[68:71]
	v_mfma_f32_16x16x32_bf16 v[60:63], v[202:205], v[174:177], v[60:63]
	v_mfma_f32_16x16x32_bf16 v[56:59], v[210:213], v[174:177], v[56:59]
	v_mfma_f32_16x16x32_bf16 v[44:47], v[202:205], v[182:185], v[44:47]
	v_mfma_f32_16x16x32_bf16 v[40:43], v[210:213], v[182:185], v[40:43]
	v_mfma_f32_16x16x32_bf16 v[36:39], v[202:205], v[190:193], v[36:39]
	v_mfma_f32_16x16x32_bf16 v[32:35], v[210:213], v[190:193], v[32:35]
	v_mfma_f32_16x16x32_bf16 v[76:79], v[206:209], v[170:173], v[76:79]
	v_mfma_f32_16x16x32_bf16 v[68:71], v[214:217], v[170:173], v[68:71]
	v_mfma_f32_16x16x32_bf16 v[60:63], v[206:209], v[178:181], v[60:63]
	v_mfma_f32_16x16x32_bf16 v[56:59], v[214:217], v[178:181], v[56:59]
	v_mfma_f32_16x16x32_bf16 v[44:47], v[206:209], v[186:189], v[44:47]
	v_mfma_f32_16x16x32_bf16 v[40:43], v[214:217], v[186:189], v[40:43]
	v_mfma_f32_16x16x32_bf16 v[36:39], v[206:209], v[198:201], v[36:39]
	v_mfma_f32_16x16x32_bf16 v[32:35], v[214:217], v[198:201], v[32:35]
	s_setprio 0
	s_mov_b32 m0, s33
	v_lshl_add_u64 v[194:195], v[220:221], 0, s[8:9]
	s_barrier
	ds_read_b128 v[166:169], v148 offset:49152
	ds_read_b128 v[170:173], v148 offset:50176
	ds_read_b128 v[174:177], v148 offset:51200
	ds_read_b128 v[178:181], v148 offset:52224
	ds_read_b128 v[182:185], v148 offset:53248
	ds_read_b128 v[186:189], v148 offset:54272
	ds_read_b128 v[190:193], v148 offset:55296
	ds_read_b128 v[198:201], v148 offset:56320
	global_load_lds_dwordx4 v[194:195], off
	v_lshl_add_u64 v[194:195], v[222:223], 0, s[8:9]
	s_mov_b32 m0, s34
	s_nop 0
	global_load_lds_dwordx4 v[194:195], off
	s_barrier
; __device__ __forceinline__ unsigned pk_bf16(float lo, float hi) { unsigned r; asm volatile("v_cvt_pk_bf16_f32 %0, %1, %2" : "=v"(r) : "v"(lo), "v"(hi)); return r; }
; __device__ __forceinline__ float sigmoidf_(float x) { return __builtin_amdgcn_rcpf(1.0f + __expf(-x)); }
; #define PG8_STAGE(bufoff, gbase, voff) do { _Pragma("unroll") for (int _i = 0; _i < 2; ++_i) \
;         __builtin_amdgcn_global_load_lds((const unsigned*)((const char*)(gbase) + (voff)[_i]), (LAS unsigned*)(lds + (bufoff) + ldsw + _i * 8192), 16, 0, 0); } while (0)
; #define PG8_WAIT_V(n) asm volatile("s_waitcnt vmcnt(" #n ")" ::: "memory")
; template <class Epi, class Sched>
; __device__ __forceinline__ void gemm_phase(LAS unsigned char* lds, const Gemm g, const Sched& S, const Epi& E) {
;     ...
;             PG8_BAR; PG8_WAIT_L(0); PG8_MMA(1, 0, At, B0); PG8_BAR; PG8_SCHED;
;             PG8_STAGE(PG8_SB(1, 1), b3 + hstepB, voffB);
;             PG8_WAIT_V(6); PG8_BAR; PG8_MMA(1, 1, At, B1); PG8_BAR;
;         }
;         if constexpr (!Epi::AFTER_DRAIN) E(acc, cur, wr, wc, fr, fq);
;     __device__ __forceinline__ void operator()(const f32x4 (&acc)[2][2][4][2], const Unit& u, int wr, int wc, int fr, int fq) const {
;         const int row0 = u.pm * 256 + wr * 64 + fr, col0 = coff + u.pn * 256 + wc * 32 + 8 * fq;
; #pragma unroll
;         for (int bj = 0; bj < 2; ++bj) {
;             const int c = col0 + bj * 128;
;             f32x4 s0, s1;
;             if (MODE == 0) { s0 = vec ? *(const f32x4*)(vec + c) : (f32x4){1.f, 1.f, 1.f, 1.f}; s1 = vec ? *(const f32x4*)(vec + c + 4) : (f32x4){1.f, 1.f, 1.f, 1.f}; }
;             else { s0 = *(const f32x4*)(vec + c); s1 = *(const f32x4*)(vec + c + 4); }
; #pragma unroll
;             for (int ai = 0; ai < 2; ++ai)
; #pragma unroll
;                 for (int m = 0; m < 4; ++m) {
;                     f32x4 v0 = acc[ai][bj][m][0], v1 = acc[ai][bj][m][1];
;                     if (MODE == 0) { v0 = v0 * s0; v1 = v1 * s1; }
;                     else {
; #pragma unroll
;                         for (int j = 0; j < 4; ++j) { v0[j] = sigmoidf_(v0[j] + s0[j]); v1[j] = sigmoidf_(v1[j] + s1[j]); } }
;                     u32x4 w; w.x = pk_bf16(v0[0], v0[1]); w.y = pk_bf16(v0[2], v0[3]); w.z = pk_bf16(v1[0], v1[1]); w.w = pk_bf16(v1[2], v1[3]);
;                     *(u32x4*)(O + (size_t)(row0 + ai * 128 + m * 16) * ldc + c) = w;
;                 }
	s_waitcnt lgkmcnt(0)
	s_setprio 1
	s_waitcnt lgkmcnt(0)
	v_mfma_f32_16x16x32_bf16 v[92:95], v[150:153], v[166:169], v[92:95]
	v_mfma_f32_16x16x32_bf16 v[88:91], v[158:161], v[166:169], v[88:91]
	v_mfma_f32_16x16x32_bf16 v[84:87], v[150:153], v[174:177], v[84:87]
	v_mfma_f32_16x16x32_bf16 v[80:83], v[158:161], v[174:177], v[80:83]
	v_mfma_f32_16x16x32_bf16 v[72:75], v[150:153], v[182:185], v[72:75]
	v_mfma_f32_16x16x32_bf16 v[64:67], v[158:161], v[182:185], v[64:67]
	v_mfma_f32_16x16x32_bf16 v[52:55], v[150:153], v[190:193], v[52:55]
	v_mfma_f32_16x16x32_bf16 v[48:51], v[158:161], v[190:193], v[48:51]
	v_mfma_f32_16x16x32_bf16 v[92:95], v[154:157], v[170:173], v[92:95]
	v_mfma_f32_16x16x32_bf16 v[88:91], v[162:165], v[170:173], v[88:91]
	v_mfma_f32_16x16x32_bf16 v[84:87], v[154:157], v[178:181], v[84:87]
	v_mfma_f32_16x16x32_bf16 v[80:83], v[162:165], v[178:181], v[80:83]
	v_mfma_f32_16x16x32_bf16 v[72:75], v[154:157], v[186:189], v[72:75]
	v_mfma_f32_16x16x32_bf16 v[64:67], v[162:165], v[186:189], v[64:67]
	v_mfma_f32_16x16x32_bf16 v[52:55], v[154:157], v[198:201], v[52:55]
	v_mfma_f32_16x16x32_bf16 v[48:51], v[162:165], v[198:201], v[48:51]
	s_setprio 0
	s_barrier
	s_add_u32 s24, s24, 0x80080
	s_addc_u32 s25, s25, 0
	s_add_i32 s26, s26, s22
	v_lshl_add_u64 v[150:151], s[24:25], 0, v[130:131]
	s_mov_b32 m0, s26
	s_nop 0
	global_load_lds_dwordx4 v[150:151], off
	v_lshl_add_u64 v[150:151], s[24:25], 0, v[134:135]
	s_add_i32 m0, s26, 0x2000
	s_nop 0
	global_load_lds_dwordx4 v[150:151], off
	s_waitcnt vmcnt(6)
	s_barrier
	s_setprio 1
	v_mfma_f32_16x16x32_bf16 v[28:31], v[202:205], v[166:169], v[28:31]
	v_mfma_f32_16x16x32_bf16 v[24:27], v[210:213], v[166:169], v[24:27]
	v_mfma_f32_16x16x32_bf16 v[20:23], v[202:205], v[174:177], v[20:23]
	v_mfma_f32_16x16x32_bf16 v[16:19], v[210:213], v[174:177], v[16:19]
	v_mfma_f32_16x16x32_bf16 v[12:15], v[202:205], v[182:185], v[12:15]
	v_mfma_f32_16x16x32_bf16 v[8:11], v[210:213], v[182:185], v[8:11]
	v_mfma_f32_16x16x32_bf16 v[4:7], v[202:205], v[190:193], v[4:7]
	v_mfma_f32_16x16x32_bf16 v[0:3], v[210:213], v[190:193], v[0:3]
	v_mfma_f32_16x16x32_bf16 v[28:31], v[206:209], v[170:173], v[28:31]
	v_mfma_f32_16x16x32_bf16 v[24:27], v[214:217], v[170:173], v[24:27]
	v_mfma_f32_16x16x32_bf16 v[20:23], v[206:209], v[178:181], v[20:23]
	v_mfma_f32_16x16x32_bf16 v[16:19], v[214:217], v[178:181], v[16:19]
	v_mfma_f32_16x16x32_bf16 v[12:15], v[206:209], v[186:189], v[12:15]
	v_mfma_f32_16x16x32_bf16 v[8:11], v[214:217], v[186:189], v[8:11]
	v_mfma_f32_16x16x32_bf16 v[4:7], v[206:209], v[198:201], v[4:7]
	v_mfma_f32_16x16x32_bf16 v[0:3], v[214:217], v[198:201], v[0:3]
	s_setprio 0
	s_add_i32 s64, s64, 2
	s_add_u32 s20, s20, 0x100
	s_addc_u32 s21, s21, 0
	s_add_u32 s62, s62, 0x100
	s_addc_u32 s63, s63, 0
	s_cmp_gt_u32 s64, 29
	s_barrier
	s_cbranch_scc0 .LBB0_121
	v_lshl_or_b32 v150, s59, 8, v146
	v_lshl_add_u32 v152, s16, 7, v144
	v_ashrrev_i32_e32 v151, 31, v150
	v_cvt_pk_bf16_f32 v124, v124, v125
	v_cvt_pk_bf16_f32 v125, v126, v127
	v_cvt_pk_bf16_f32 v126, v120, v121
	v_mov_b64_e32 v[120:121], s[48:49]
	v_cvt_pk_bf16_f32 v127, v122, v123
	v_mad_i64_i32 v[122:123], s[4:5], v152, s58, v[120:121]
	v_lshlrev_b64 v[150:151], 1, v[150:151]
	v_lshl_add_u64 v[122:123], v[122:123], 0, v[150:151]
	global_store_dwordx4 v[122:123], v[124:127], off
	v_cvt_pk_bf16_f32 v116, v116, v117
	v_cvt_pk_bf16_f32 v117, v118, v119
	v_cvt_pk_bf16_f32 v118, v112, v113
	v_or_b32_e32 v112, 16, v152
	v_mad_i64_i32 v[112:113], s[4:5], v112, s58, v[120:121]
	v_lshl_add_u64 v[112:113], v[112:113], 0, v[150:151]
	v_cvt_pk_bf16_f32 v119, v114, v115
	global_store_dwordx4 v[112:113], v[116:119], off
	v_cvt_pk_bf16_f32 v108, v108, v109
	v_cvt_pk_bf16_f32 v109, v110, v111
	v_cvt_pk_bf16_f32 v110, v104, v105
	v_or_b32_e32 v104, 32, v152
	v_mad_i64_i32 v[104:105], s[4:5], v104, s58, v[120:121]
	v_lshl_add_u64 v[104:105], v[104:105], 0, v[150:151]
	v_cvt_pk_bf16_f32 v111, v106, v107
	global_store_dwordx4 v[104:105], v[108:111], off
	v_cvt_pk_bf16_f32 v100, v100, v101
	v_cvt_pk_bf16_f32 v101, v102, v103
	v_cvt_pk_bf16_f32 v102, v96, v97
	v_or_b32_e32 v96, 48, v152
	v_mad_i64_i32 v[96:97], s[4:5], v96, s58, v[120:121]
	v_cvt_pk_bf16_f32 v103, v98, v99
	v_lshl_add_u64 v[96:97], v[96:97], 0, v[150:151]
	v_add_u32_e32 v98, 0x80, v152
	global_store_dwordx4 v[96:97], v[100:103], off
	v_cvt_pk_bf16_f32 v92, v92, v93
	v_cvt_pk_bf16_f32 v93, v94, v95
	v_cvt_pk_bf16_f32 v94, v88, v89
	v_mad_i64_i32 v[88:89], s[4:5], v98, s58, v[120:121]
	v_lshl_add_u64 v[88:89], v[88:89], 0, v[150:151]
	v_cvt_pk_bf16_f32 v95, v90, v91
	global_store_dwordx4 v[88:89], v[92:95], off
	v_cvt_pk_bf16_f32 v84, v84, v85
	v_cvt_pk_bf16_f32 v85, v86, v87
	v_cvt_pk_bf16_f32 v86, v80, v81
	v_add_u32_e32 v80, 0x90, v152
	v_mad_i64_i32 v[80:81], s[4:5], v80, s58, v[120:121]
	v_lshl_add_u64 v[80:81], v[80:81], 0, v[150:151]
	v_cvt_pk_bf16_f32 v87, v82, v83
	global_store_dwordx4 v[80:81], v[84:87], off
	v_cvt_pk_bf16_f32 v72, v72, v73
	v_cvt_pk_bf16_f32 v73, v74, v75
	v_cvt_pk_bf16_f32 v74, v64, v65
	v_add_u32_e32 v64, 0xa0, v152
	v_mad_i64_i32 v[64:65], s[4:5], v64, s58, v[120:121]
	v_lshl_add_u64 v[64:65], v[64:65], 0, v[150:151]
	v_cvt_pk_bf16_f32 v75, v66, v67
	global_store_dwordx4 v[64:65], v[72:75], off
	v_cvt_pk_bf16_f32 v52, v52, v53
	v_cvt_pk_bf16_f32 v53, v54, v55
	v_cvt_pk_bf16_f32 v54, v48, v49
	v_add_u32_e32 v48, 0xb0, v152
	v_mad_i64_i32 v[48:49], s[4:5], v48, s58, v[120:121]
	v_lshl_add_u64 v[66:67], v[48:49], 0, v[150:151]
	v_cvt_pk_bf16_f32 v55, v50, v51
	global_store_dwordx4 v[66:67], v[52:55], off
	v_cvt_pk_bf16_f32 v48, v76, v77
	v_cvt_pk_bf16_f32 v49, v78, v79
; #define PG8_BAR __builtin_amdgcn_s_barrier()
; template <class Epi, class Sched>
; __device__ __forceinline__ void gemm_phase(LAS unsigned char* lds, const Gemm g, const Sched& S, const Epi& E) {
;     ...
;         for (int t = 0; t < nt; t += 2) {
;             const bool last = (t == nt - 2);
;             const char* a1 = cA + (size_t)(t + 1) * kstep;
;             const char* a2 = last ? nA : cA + (size_t)(t + 2) * kstep; const char* b2 = last ? nB : cB + (size_t)(t + 2) * kstep;
;             const char* a3 = a2 + kstep; const char* b3 = b2 + kstep;
;             PG8_LDB(B0, 0, 0); PG8_SCHED; PG8_LDA(At, 0, 0); PG8_STAGE(PG8_SA(1, 1), a1 + hstepA, voffA);
;             PG8_WAIT_L(8); PG8_BAR; PG8_WAIT_L(0); PG8_MMA(0, 0, At, B0); PG8_BAR; PG8_SCHED;
;             PG8_LDB(B1, 0, 1); PG8_STAGE(PG8_SB(0, 0), b2, voffB);
;             PG8_BAR; PG8_WAIT_L(0); PG8_MMA(0, 1, At, B1); PG8_BAR;
;             PG8_LDA(At, 0, 1); PG8_STAGE(PG8_SA(0, 0), a2, voffA);
;             PG8_BAR; PG8_WAIT_L(0); PG8_MMA(1, 0, At, B0); PG8_BAR; PG8_SCHED;
;             PG8_STAGE(PG8_SB(0, 1), b2 + hstepB, voffB);
;             PG8_WAIT_V(6); PG8_BAR; PG8_MMA(1, 1, At, B1); PG8_BAR;
;     __device__ __forceinline__ void operator()(const f32x4 (&acc)[2][2][4][2], const Unit& u, int wr, int wc, int fr, int fq) const {
;         const int row0 = u.pm * 256 + wr * 64 + fr, col0 = coff + u.pn * 256 + wc * 32 + 8 * fq;
; #pragma unroll
;         for (int bj = 0; bj < 2; ++bj) {
;             const int c = col0 + bj * 128;
;             f32x4 s0, s1;
;             if (MODE == 0) { s0 = vec ? *(const f32x4*)(vec + c) : (f32x4){1.f, 1.f, 1.f, 1.f}; s1 = vec ? *(const f32x4*)(vec + c + 4) : (f32x4){1.f, 1.f, 1.f, 1.f}; }
;             else { s0 = *(const f32x4*)(vec + c); s1 = *(const f32x4*)(vec + c + 4); }
; #pragma unroll
;             for (int ai = 0; ai < 2; ++ai)
; #pragma unroll
;                 for (int m = 0; m < 4; ++m) {
;                     f32x4 v0 = acc[ai][bj][m][0], v1 = acc[ai][bj][m][1];
;                     if (MODE == 0) { v0 = v0 * s0; v1 = v1 * s1; }
;                     else {
; #pragma unroll
;                         for (int j = 0; j < 4; ++j) { v0[j] = sigmoidf_(v0[j] + s0[j]); v1[j] = sigmoidf_(v1[j] + s1[j]); } }
;                     u32x4 w; w.x = pk_bf16(v0[0], v0[1]); w.y = pk_bf16(v0[2], v0[3]); w.z = pk_bf16(v1[0], v1[1]); w.w = pk_bf16(v1[2], v1[3]);
	v_cvt_pk_bf16_f32 v50, v68, v69
	v_cvt_pk_bf16_f32 v51, v70, v71
	s_and_b64 vcc, exec, s[6:7]
	s_mov_b32 s59, s10
	s_mov_b32 s16, s12
	s_mov_b32 s70, s71
	s_mov_b64 s[24:25], s[18:19]
	s_mov_b64 s[20:21], s[14:15]
	global_store_dwordx4 v[122:123], v[48:51], off offset:256
	s_nop 1
	v_cvt_pk_bf16_f32 v48, v60, v61
	v_cvt_pk_bf16_f32 v49, v62, v63
	v_cvt_pk_bf16_f32 v50, v56, v57
	v_cvt_pk_bf16_f32 v51, v58, v59
	global_store_dwordx4 v[112:113], v[48:51], off offset:256
	v_cvt_pk_bf16_f32 v44, v44, v45
	v_cvt_pk_bf16_f32 v45, v46, v47
	v_cvt_pk_bf16_f32 v46, v40, v41
	v_cvt_pk_bf16_f32 v47, v42, v43
	global_store_dwordx4 v[104:105], v[44:47], off offset:256
	v_cvt_pk_bf16_f32 v36, v36, v37
	v_cvt_pk_bf16_f32 v37, v38, v39
	v_cvt_pk_bf16_f32 v38, v32, v33
	v_cvt_pk_bf16_f32 v39, v34, v35
	global_store_dwordx4 v[96:97], v[36:39], off offset:256
	v_cvt_pk_bf16_f32 v28, v28, v29
	v_cvt_pk_bf16_f32 v29, v30, v31
	v_cvt_pk_bf16_f32 v30, v24, v25
	v_cvt_pk_bf16_f32 v31, v26, v27
	global_store_dwordx4 v[88:89], v[28:31], off offset:256
	v_cvt_pk_bf16_f32 v20, v20, v21
	v_cvt_pk_bf16_f32 v21, v22, v23
	v_cvt_pk_bf16_f32 v22, v16, v17
	v_cvt_pk_bf16_f32 v23, v18, v19
	global_store_dwordx4 v[80:81], v[20:23], off offset:256
	v_cvt_pk_bf16_f32 v12, v12, v13
	v_cvt_pk_bf16_f32 v13, v14, v15
	v_cvt_pk_bf16_f32 v14, v8, v9
	v_cvt_pk_bf16_f32 v15, v10, v11
	global_store_dwordx4 v[64:65], v[12:15], off offset:256
	v_cvt_pk_bf16_f32 v4, v4, v5
	v_cvt_pk_bf16_f32 v5, v6, v7
	v_cvt_pk_bf16_f32 v6, v0, v1
	v_cvt_pk_bf16_f32 v7, v2, v3
	global_store_dwordx4 v[66:67], v[4:7], off offset:256
	s_cbranch_vccz .LBB0_114
.Lp1_done:
	s_waitcnt vmcnt(0)
	s_cmpk_gt_u32 s0, 0xff
	s_cbranch_scc1 .LBB0_125
	s_barrier
.LBB0_125:
	s_barrier
	s_branch .LBB0_126
.Lp1h_loop:
	ds_read_b128 v[150:153], v147
	ds_read_b128 v[154:157], v147 offset:1024
	ds_read_b128 v[158:161], v147 offset:2048
	ds_read_b128 v[162:165], v147 offset:3072
	s_add_u32 s24, s20, 0xfff80080
	s_addc_u32 s25, s21, -1
	s_cmp_eq_u32 s64, 28
	s_cselect_b32 s27, s4, s25
	s_cselect_b32 s26, s5, s24
	s_cselect_b32 s25, s11, s63
	s_cselect_b32 s24, s13, s62
	v_lshl_add_u64 v[194:195], s[20:21], 0, v[136:137]
	s_add_i32 m0, s17, 0xc000
	ds_read_b128 v[166:169], v148
	ds_read_b128 v[170:173], v148 offset:1024
	ds_read_b128 v[174:177], v148 offset:2048
	ds_read_b128 v[178:181], v148 offset:3072
	ds_read_b128 v[182:185], v148 offset:4096
	ds_read_b128 v[186:189], v148 offset:5120
	ds_read_b128 v[190:193], v148 offset:6144
	ds_read_b128 v[198:201], v148 offset:7168
	global_load_lds_dwordx4 v[194:195], off
	v_lshl_add_u64 v[194:195], s[20:21], 0, v[138:139]
	s_add_i32 m0, s17, 0xe000
	s_nop 0
	global_load_lds_dwordx4 v[194:195], off
	s_waitcnt lgkmcnt(8)
	s_barrier
	s_waitcnt lgkmcnt(0)
	s_setprio 1
	s_waitcnt lgkmcnt(0)
	v_mfma_f32_16x16x32_bf16 v[124:127], v[150:153], v[166:169], v[124:127]
	v_mfma_f32_16x16x32_bf16 v[120:123], v[158:161], v[166:169], v[120:123]
	v_mfma_f32_16x16x32_bf16 v[116:119], v[150:153], v[174:177], v[116:119]
	v_mfma_f32_16x16x32_bf16 v[112:115], v[158:161], v[174:177], v[112:115]
	v_mfma_f32_16x16x32_bf16 v[108:111], v[150:153], v[182:185], v[108:111]
	v_mfma_f32_16x16x32_bf16 v[104:107], v[158:161], v[182:185], v[104:107]
	v_mfma_f32_16x16x32_bf16 v[100:103], v[150:153], v[190:193], v[100:103]
	v_mfma_f32_16x16x32_bf16 v[96:99], v[158:161], v[190:193], v[96:99]
	v_mfma_f32_16x16x32_bf16 v[124:127], v[154:157], v[170:173], v[124:127]
	v_mfma_f32_16x16x32_bf16 v[120:123], v[162:165], v[170:173], v[120:123]
	v_mfma_f32_16x16x32_bf16 v[116:119], v[154:157], v[178:181], v[116:119]
	v_mfma_f32_16x16x32_bf16 v[112:115], v[162:165], v[178:181], v[112:115]
	v_mfma_f32_16x16x32_bf16 v[108:111], v[154:157], v[186:189], v[108:111]
	v_mfma_f32_16x16x32_bf16 v[104:107], v[162:165], v[186:189], v[104:107]
	v_mfma_f32_16x16x32_bf16 v[100:103], v[154:157], v[198:201], v[100:103]
	v_mfma_f32_16x16x32_bf16 v[96:99], v[162:165], v[198:201], v[96:99]
	s_setprio 0
	s_barrier
	s_add_i32 s65, s50, s22
	v_lshl_add_u64 v[194:195], s[24:25], 0, v[130:131]
	s_mov_b32 m0, s65
	ds_read_b128 v[202:205], v149
	ds_read_b128 v[206:209], v149 offset:1024
	ds_read_b128 v[210:213], v149 offset:2048
	ds_read_b128 v[214:217], v149 offset:3072
	global_load_lds_dwordx4 v[194:195], off
	v_lshl_add_u64 v[218:219], s[24:25], 0, v[134:135]
	s_add_i32 m0, s65, 0x2000
	s_nop 0
	global_load_lds_dwordx4 v[218:219], off
	s_barrier
	s_waitcnt lgkmcnt(0)
	s_setprio 1
	s_waitcnt lgkmcnt(0)
	v_mfma_f32_16x16x32_bf16 v[76:79], v[202:205], v[166:169], v[76:79]
	v_mfma_f32_16x16x32_bf16 v[68:71], v[210:213], v[166:169], v[68:71]
	v_mfma_f32_16x16x32_bf16 v[60:63], v[202:205], v[174:177], v[60:63]
	v_mfma_f32_16x16x32_bf16 v[56:59], v[210:213], v[174:177], v[56:59]
	v_mfma_f32_16x16x32_bf16 v[44:47], v[202:205], v[182:185], v[44:47]
	v_mfma_f32_16x16x32_bf16 v[40:43], v[210:213], v[182:185], v[40:43]
	v_mfma_f32_16x16x32_bf16 v[36:39], v[202:205], v[190:193], v[36:39]
	v_mfma_f32_16x16x32_bf16 v[32:35], v[210:213], v[190:193], v[32:35]
	v_mfma_f32_16x16x32_bf16 v[76:79], v[206:209], v[170:173], v[76:79]
	v_mfma_f32_16x16x32_bf16 v[68:71], v[214:217], v[170:173], v[68:71]
	v_mfma_f32_16x16x32_bf16 v[60:63], v[206:209], v[178:181], v[60:63]
	v_mfma_f32_16x16x32_bf16 v[56:59], v[214:217], v[178:181], v[56:59]
	v_mfma_f32_16x16x32_bf16 v[44:47], v[206:209], v[186:189], v[44:47]
	v_mfma_f32_16x16x32_bf16 v[40:43], v[214:217], v[186:189], v[40:43]
	v_mfma_f32_16x16x32_bf16 v[36:39], v[206:209], v[198:201], v[36:39]
	v_mfma_f32_16x16x32_bf16 v[32:35], v[214:217], v[198:201], v[32:35]
	s_setprio 0
	s_mov_b32 m0, s17
	v_lshl_add_u64 v[220:221], s[26:27], 0, v[128:129]
	s_barrier
; #define PG8_STAGE(bufoff, gbase, voff) do { _Pragma("unroll") for (int _i = 0; _i < 2; ++_i) \
;         __builtin_amdgcn_global_load_lds((const unsigned*)((const char*)(gbase) + (voff)[_i]), (LAS unsigned*)(lds + (bufoff) + ldsw + _i * 8192), 16, 0, 0); } while (0)
; #define PG8_LDA(dst, b, h) do { _Pragma("unroll") for (int m = 0; m < 4; ++m) _Pragma("unroll") for (int k = 0; k < 2; ++k) dst[m][k] = *(const LAS bf16x8*)(lds + PG8_SA(b, h) + aoff + m * 2048 + k * 1024); } while (0)
; #define PG8_LDB(dst, b, h) do { _Pragma("unroll") for (int n = 0; n < 2; ++n) _Pragma("unroll") for (int k = 0; k < 2; ++k) dst[n][k] = *(const LAS bf16x8*)(lds + PG8_SB(b, h) + boff + n * 2048 + k * 1024); } while (0)
; #define PG8_MMA(ai, bj, At, Bt) do { __builtin_amdgcn_s_setprio(1); _Pragma("unroll") for (int m = 0; m < 4; ++m) _Pragma("unroll") for (int n = 0; n < 2; ++n) _Pragma("unroll") for (int k = 0; k < 2; ++k) \
;         acc[ai][bj][m][n] = __builtin_amdgcn_mfma_f32_16x16x32_bf16(Bt[n][k], At[m][k], acc[ai][bj][m][n], 0, 0, 0); __builtin_amdgcn_s_setprio(0); } while (0)
; #define PG8_WAIT_V(n) asm volatile("s_waitcnt vmcnt(" #n ")" ::: "memory")
; #define PG8_WAIT_L(n) asm volatile("s_waitcnt lgkmcnt(" #n ")" ::: "memory")
; #define PG8_BAR __builtin_amdgcn_s_barrier()
; #define PG8_SCHED __builtin_amdgcn_sched_barrier(0)
; template <class Epi, class Sched>
; __device__ __forceinline__ void gemm_phase(LAS unsigned char* lds, const Gemm g, const Sched& S, const Epi& E) {
;     ...
;             PG8_LDA(At, 0, 1); PG8_STAGE(PG8_SA(0, 0), a2, voffA);
;             PG8_BAR; PG8_WAIT_L(0); PG8_MMA(1, 0, At, B0); PG8_BAR; PG8_SCHED;
;             PG8_STAGE(PG8_SB(0, 1), b2 + hstepB, voffB);
;             PG8_WAIT_V(6); PG8_BAR; PG8_MMA(1, 1, At, B1); PG8_BAR;
;             PG8_LDB(B0, 1, 0); PG8_SCHED; PG8_LDA(At, 1, 0); PG8_STAGE(PG8_SA(0, 1), a2 + hstepA, voffA);
;             PG8_WAIT_L(8); PG8_BAR; PG8_WAIT_L(0); PG8_MMA(0, 0, At, B0); PG8_BAR; PG8_SCHED;
;             PG8_LDB(B1, 1, 1); PG8_STAGE(PG8_SB(1, 0), b3, voffB);
;             PG8_BAR; PG8_WAIT_L(0); PG8_MMA(0, 1, At, B1); PG8_BAR;
;             PG8_LDA(At, 1, 1); PG8_STAGE(PG8_SA(1, 0), a3, voffA);
;             PG8_BAR; PG8_WAIT_L(0); PG8_MMA(1, 0, At, B0); PG8_BAR; PG8_SCHED;
;             PG8_STAGE(PG8_SB(1, 1), b3 + hstepB, voffB);
;             PG8_WAIT_V(6); PG8_BAR; PG8_MMA(1, 1, At, B1); PG8_BAR;
	global_load_lds_dwordx4 v[220:221], off
	v_lshl_add_u64 v[222:223], s[26:27], 0, v[132:133]
	s_mov_b32 m0, s23
	s_nop 0
	global_load_lds_dwordx4 v[222:223], off
	s_barrier
	s_waitcnt lgkmcnt(0)
	s_setprio 1
	s_waitcnt lgkmcnt(0)
	s_setprio 0
	s_barrier
	s_add_u32 s68, s24, 0x80000
	s_addc_u32 s69, s25, 0
	s_add_i32 s65, s51, s22
	v_lshl_add_u64 v[150:151], s[68:69], 0, v[130:131]
	s_mov_b32 m0, s65
	s_nop 0
	global_load_lds_dwordx4 v[150:151], off
	v_lshl_add_u64 v[150:151], s[68:69], 0, v[134:135]
	s_add_i32 m0, s65, 0x2000
	s_nop 0
	global_load_lds_dwordx4 v[150:151], off
	s_waitcnt vmcnt(6)
	s_barrier
	s_setprio 1
	s_setprio 0
	s_add_i32 s65, 0, 0x18000
	v_add_u32_e32 v162, s65, v145
	s_barrier
	ds_read_b128 v[150:153], v162
	ds_read_b128 v[154:157], v162 offset:1024
	ds_read_b128 v[158:161], v162 offset:2048
	ds_read_b128 v[162:165], v162 offset:3072
	s_add_u32 s26, s26, 0x80000
	s_addc_u32 s27, s27, 0
	s_mov_b32 m0, s29
	v_lshl_add_u64 v[202:203], s[26:27], 0, v[128:129]
	ds_read_b128 v[166:169], v148 offset:32768
	ds_read_b128 v[170:173], v148 offset:33792
	ds_read_b128 v[174:177], v148 offset:34816
	ds_read_b128 v[178:181], v148 offset:35840
	ds_read_b128 v[182:185], v148 offset:36864
	ds_read_b128 v[186:189], v148 offset:37888
	ds_read_b128 v[190:193], v148 offset:38912
	ds_read_b128 v[198:201], v148 offset:39936
	global_load_lds_dwordx4 v[202:203], off
	v_lshl_add_u64 v[202:203], s[26:27], 0, v[132:133]
	s_mov_b32 m0, s30
	s_nop 0
	global_load_lds_dwordx4 v[202:203], off
	s_waitcnt lgkmcnt(8)
	s_barrier
	s_waitcnt lgkmcnt(0)
	s_setprio 1
	s_waitcnt lgkmcnt(0)
	v_mfma_f32_16x16x32_bf16 v[124:127], v[150:153], v[166:169], v[124:127]
	v_mfma_f32_16x16x32_bf16 v[120:123], v[158:161], v[166:169], v[120:123]
	v_mfma_f32_16x16x32_bf16 v[116:119], v[150:153], v[174:177], v[116:119]
	v_mfma_f32_16x16x32_bf16 v[112:115], v[158:161], v[174:177], v[112:115]
	v_mfma_f32_16x16x32_bf16 v[108:111], v[150:153], v[182:185], v[108:111]
	v_mfma_f32_16x16x32_bf16 v[104:107], v[158:161], v[182:185], v[104:107]
	v_mfma_f32_16x16x32_bf16 v[100:103], v[150:153], v[190:193], v[100:103]
	v_mfma_f32_16x16x32_bf16 v[96:99], v[158:161], v[190:193], v[96:99]
	v_mfma_f32_16x16x32_bf16 v[124:127], v[154:157], v[170:173], v[124:127]
	v_mfma_f32_16x16x32_bf16 v[120:123], v[162:165], v[170:173], v[120:123]
	v_mfma_f32_16x16x32_bf16 v[116:119], v[154:157], v[178:181], v[116:119]
	v_mfma_f32_16x16x32_bf16 v[112:115], v[162:165], v[178:181], v[112:115]
	v_mfma_f32_16x16x32_bf16 v[108:111], v[154:157], v[186:189], v[108:111]
	v_mfma_f32_16x16x32_bf16 v[104:107], v[162:165], v[186:189], v[104:107]
	v_mfma_f32_16x16x32_bf16 v[100:103], v[154:157], v[198:201], v[100:103]
	v_mfma_f32_16x16x32_bf16 v[96:99], v[162:165], v[198:201], v[96:99]
	s_setprio 0
	s_barrier
	s_add_i32 s26, 0, 0x1c000
	s_add_i32 s27, s65, s22
	v_add_u32_e32 v197, s26, v145
	v_lshl_add_u64 v[194:195], v[194:195], 0, s[8:9]
	s_mov_b32 m0, s27
	ds_read_b128 v[202:205], v197
	ds_read_b128 v[206:209], v197 offset:1024
	ds_read_b128 v[210:213], v197 offset:2048
	ds_read_b128 v[214:217], v197 offset:3072
	global_load_lds_dwordx4 v[194:195], off
	v_lshl_add_u64 v[194:195], v[218:219], 0, s[8:9]
	s_add_i32 m0, s27, 0x2000
	s_nop 0
	global_load_lds_dwordx4 v[194:195], off
	s_barrier
	s_waitcnt lgkmcnt(0)
	s_setprio 1
	s_waitcnt lgkmcnt(0)
	v_mfma_f32_16x16x32_bf16 v[76:79], v[202:205], v[166:169], v[76:79]
	v_mfma_f32_16x16x32_bf16 v[68:71], v[210:213], v[166:169], v[68:71]
	v_mfma_f32_16x16x32_bf16 v[60:63], v[202:205], v[174:177], v[60:63]
	v_mfma_f32_16x16x32_bf16 v[56:59], v[210:213], v[174:177], v[56:59]
	v_mfma_f32_16x16x32_bf16 v[44:47], v[202:205], v[182:185], v[44:47]
	v_mfma_f32_16x16x32_bf16 v[40:43], v[210:213], v[182:185], v[40:43]
	v_mfma_f32_16x16x32_bf16 v[36:39], v[202:205], v[190:193], v[36:39]
	v_mfma_f32_16x16x32_bf16 v[32:35], v[210:213], v[190:193], v[32:35]
	v_mfma_f32_16x16x32_bf16 v[76:79], v[206:209], v[170:173], v[76:79]
	v_mfma_f32_16x16x32_bf16 v[68:71], v[214:217], v[170:173], v[68:71]
	v_mfma_f32_16x16x32_bf16 v[60:63], v[206:209], v[178:181], v[60:63]
	v_mfma_f32_16x16x32_bf16 v[56:59], v[214:217], v[178:181], v[56:59]
	v_mfma_f32_16x16x32_bf16 v[44:47], v[206:209], v[186:189], v[44:47]
	v_mfma_f32_16x16x32_bf16 v[40:43], v[214:217], v[186:189], v[40:43]
	v_mfma_f32_16x16x32_bf16 v[36:39], v[206:209], v[198:201], v[36:39]
	v_mfma_f32_16x16x32_bf16 v[32:35], v[214:217], v[198:201], v[32:35]
	s_setprio 0
	s_mov_b32 m0, s33
	v_lshl_add_u64 v[194:195], v[220:221], 0, s[8:9]
	s_barrier
; __device__ __forceinline__ unsigned pk_bf16(float lo, float hi) { unsigned r; asm volatile("v_cvt_pk_bf16_f32 %0, %1, %2" : "=v"(r) : "v"(lo), "v"(hi)); return r; }
; __device__ __forceinline__ float sigmoidf_(float x) { return __builtin_amdgcn_rcpf(1.0f + __expf(-x)); }
; #define PG8_WAIT_V(n) asm volatile("s_waitcnt vmcnt(" #n ")" ::: "memory")
; #define PG8_WAIT_L(n) asm volatile("s_waitcnt lgkmcnt(" #n ")" ::: "memory")
; template <class Epi, class Sched>
; __device__ __forceinline__ void gemm_phase(LAS unsigned char* lds, const Gemm g, const Sched& S, const Epi& E) {
;     ...
;             PG8_BAR; PG8_WAIT_L(0); PG8_MMA(0, 1, At, B1); PG8_BAR;
;             PG8_LDA(At, 1, 1); PG8_STAGE(PG8_SA(1, 0), a3, voffA);
;             PG8_BAR; PG8_WAIT_L(0); PG8_MMA(1, 0, At, B0); PG8_BAR; PG8_SCHED;
;             PG8_STAGE(PG8_SB(1, 1), b3 + hstepB, voffB);
;             PG8_WAIT_V(6); PG8_BAR; PG8_MMA(1, 1, At, B1); PG8_BAR;
;         }
;         if constexpr (!Epi::AFTER_DRAIN) E(acc, cur, wr, wc, fr, fq);
;         if (!has_next) break;
;     __device__ __forceinline__ void operator()(const f32x4 (&acc)[2][2][4][2], const Unit& u, int wr, int wc, int fr, int fq) const {
;         const int row0 = u.pm * 256 + wr * 64 + fr, col0 = coff + u.pn * 256 + wc * 32 + 8 * fq;
; #pragma unroll
;         for (int bj = 0; bj < 2; ++bj) {
;             const int c = col0 + bj * 128;
;             f32x4 s0, s1;
;             if (MODE == 0) { s0 = vec ? *(const f32x4*)(vec + c) : (f32x4){1.f, 1.f, 1.f, 1.f}; s1 = vec ? *(const f32x4*)(vec + c + 4) : (f32x4){1.f, 1.f, 1.f, 1.f}; }
;             else { s0 = *(const f32x4*)(vec + c); s1 = *(const f32x4*)(vec + c + 4); }
; #pragma unroll
;             for (int ai = 0; ai < 2; ++ai)
; #pragma unroll
;                 for (int m = 0; m < 4; ++m) {
;                     f32x4 v0 = acc[ai][bj][m][0], v1 = acc[ai][bj][m][1];
;                     if (MODE == 0) { v0 = v0 * s0; v1 = v1 * s1; }
;                     else {
; #pragma unroll
;                         for (int j = 0; j < 4; ++j) { v0[j] = sigmoidf_(v0[j] + s0[j]); v1[j] = sigmoidf_(v1[j] + s1[j]); } }
;                     u32x4 w; w.x = pk_bf16(v0[0], v0[1]); w.y = pk_bf16(v0[2], v0[3]); w.z = pk_bf16(v1[0], v1[1]); w.w = pk_bf16(v1[2], v1[3]);
;                     *(u32x4*)(O + (size_t)(row0 + ai * 128 + m * 16) * ldc + c) = w;
;                 }
	global_load_lds_dwordx4 v[194:195], off
	v_lshl_add_u64 v[194:195], v[222:223], 0, s[8:9]
	s_mov_b32 m0, s34
	s_nop 0
	global_load_lds_dwordx4 v[194:195], off
	s_barrier
	s_waitcnt lgkmcnt(0)
	s_setprio 1
	s_waitcnt lgkmcnt(0)
	s_setprio 0
	s_barrier
	s_add_u32 s24, s24, 0x80080
	s_addc_u32 s25, s25, 0
	s_add_i32 s26, s26, s22
	v_lshl_add_u64 v[150:151], s[24:25], 0, v[130:131]
	s_mov_b32 m0, s26
	s_nop 0
	global_load_lds_dwordx4 v[150:151], off
	v_lshl_add_u64 v[150:151], s[24:25], 0, v[134:135]
	s_add_i32 m0, s26, 0x2000
	s_nop 0
	global_load_lds_dwordx4 v[150:151], off
	s_waitcnt vmcnt(6)
	s_barrier
	s_setprio 1
	s_setprio 0
	s_add_i32 s64, s64, 2
	s_add_u32 s20, s20, 0x100
	s_addc_u32 s21, s21, 0
	s_add_u32 s62, s62, 0x100
	s_addc_u32 s63, s63, 0
	s_cmp_gt_u32 s64, 29
	s_barrier
	s_cbranch_scc0 .Lp1h_loop
	v_lshl_or_b32 v150, s59, 8, v146
	v_lshl_add_u32 v152, s16, 7, v144
	v_ashrrev_i32_e32 v151, 31, v150
	v_cvt_pk_bf16_f32 v124, v124, v125
	v_cvt_pk_bf16_f32 v125, v126, v127
	v_cvt_pk_bf16_f32 v126, v120, v121
	v_mov_b64_e32 v[120:121], s[48:49]
	v_cvt_pk_bf16_f32 v127, v122, v123
	v_mad_i64_i32 v[122:123], s[4:5], v152, s58, v[120:121]
	v_lshlrev_b64 v[150:151], 1, v[150:151]
	v_lshl_add_u64 v[122:123], v[122:123], 0, v[150:151]
	global_store_dwordx4 v[122:123], v[124:127], off
	v_cvt_pk_bf16_f32 v116, v116, v117
	v_cvt_pk_bf16_f32 v117, v118, v119
	v_cvt_pk_bf16_f32 v118, v112, v113
	v_or_b32_e32 v112, 16, v152
	v_mad_i64_i32 v[112:113], s[4:5], v112, s58, v[120:121]
	v_lshl_add_u64 v[112:113], v[112:113], 0, v[150:151]
	v_cvt_pk_bf16_f32 v119, v114, v115
	global_store_dwordx4 v[112:113], v[116:119], off
	v_cvt_pk_bf16_f32 v108, v108, v109
	v_cvt_pk_bf16_f32 v109, v110, v111
	v_cvt_pk_bf16_f32 v110, v104, v105
	v_or_b32_e32 v104, 32, v152
	v_mad_i64_i32 v[104:105], s[4:5], v104, s58, v[120:121]
	v_lshl_add_u64 v[104:105], v[104:105], 0, v[150:151]
	v_cvt_pk_bf16_f32 v111, v106, v107
	global_store_dwordx4 v[104:105], v[108:111], off
	v_cvt_pk_bf16_f32 v100, v100, v101
	v_cvt_pk_bf16_f32 v101, v102, v103
	v_cvt_pk_bf16_f32 v102, v96, v97
	v_or_b32_e32 v96, 48, v152
	v_mad_i64_i32 v[96:97], s[4:5], v96, s58, v[120:121]
	v_cvt_pk_bf16_f32 v103, v98, v99
	v_lshl_add_u64 v[96:97], v[96:97], 0, v[150:151]
	global_store_dwordx4 v[96:97], v[100:103], off
	v_cvt_pk_bf16_f32 v48, v76, v77
	v_cvt_pk_bf16_f32 v49, v78, v79
	v_cvt_pk_bf16_f32 v50, v68, v69
	v_cvt_pk_bf16_f32 v51, v70, v71
	global_store_dwordx4 v[122:123], v[48:51], off offset:256
	s_nop 1
	v_cvt_pk_bf16_f32 v48, v60, v61
	v_cvt_pk_bf16_f32 v49, v62, v63
	v_cvt_pk_bf16_f32 v50, v56, v57
	v_cvt_pk_bf16_f32 v51, v58, v59
	global_store_dwordx4 v[112:113], v[48:51], off offset:256
	v_cvt_pk_bf16_f32 v44, v44, v45
	v_cvt_pk_bf16_f32 v45, v46, v47
	v_cvt_pk_bf16_f32 v46, v40, v41
	v_cvt_pk_bf16_f32 v47, v42, v43
	global_store_dwordx4 v[104:105], v[44:47], off offset:256
	v_cvt_pk_bf16_f32 v36, v36, v37
	v_cvt_pk_bf16_f32 v37, v38, v39
	v_cvt_pk_bf16_f32 v38, v32, v33
	v_cvt_pk_bf16_f32 v39, v34, v35
	global_store_dwordx4 v[96:97], v[36:39], off offset:256
	s_branch .Lp1_done
	s_nop 0
	s_nop 0
	s_nop 0
	s_nop 0
	s_nop 0
	s_nop 0
	s_nop 0
	s_nop 0
	s_nop 0
	s_nop 0
	s_nop 0
	s_nop 0
	s_nop 0
	s_nop 0
	s_nop 0
	s_nop 0
	s_nop 0
	s_nop 0
	s_nop 0
	s_nop 0
	s_nop 0
	s_nop 0
	s_nop 0
	s_nop 0
	s_nop 0
	s_nop 0
	s_nop 0
	s_nop 0
	s_nop 0
